# saddr-form K-loop DMA loads on top of the 64-byte aligned loop heads (A/B against the aligned-only version)
# baseline (speedup 1.0000x reference)
.LBB0_196:
	s_ashr_i32 s79, s78, 31
	s_lshl_b64 s[12:13], s[78:79], 19
	s_add_u32 s80, s19, s12
	s_addc_u32 s81, s66, s13
	s_and_b64 s[12:13], s[6:7], exec
	s_cselect_b32 s15, s81, s9
	s_cselect_b32 s23, s80, s8
	s_ashr_i32 s77, s76, 31
	s_lshl_b64 s[12:13], s[76:77], 19
	s_add_u32 s82, s67, s12
	s_addc_u32 s83, s88, s13
	s_and_b64 s[12:13], s[6:7], exec
	s_cselect_b32 s77, s83, s85
	s_cselect_b32 s79, s82, s84
	s_add_u32 s8, s8, 0x40080
	s_addc_u32 s9, s9, 0
	s_add_u32 vcc_lo, s84, 0x100
	v_mov_b32_e32 v2, 0
	s_addc_u32 vcc_hi, s85, 0
	s_mov_b32 s12, -2
	v_mov_b32_e32 v3, v2
	v_mov_b32_e32 v4, v2
	v_mov_b32_e32 v5, v2
	v_mov_b32_e32 v6, v2
	v_mov_b32_e32 v7, v2
	v_mov_b32_e32 v8, v2
	v_mov_b32_e32 v9, v2
	v_mov_b32_e32 v18, v2
	v_mov_b32_e32 v19, v2
	v_mov_b32_e32 v20, v2
	v_mov_b32_e32 v21, v2
	v_mov_b32_e32 v22, v2
	v_mov_b32_e32 v23, v2
	v_mov_b32_e32 v24, v2
	v_mov_b32_e32 v25, v2
	v_mov_b32_e32 v50, v2
	v_mov_b32_e32 v51, v2
	v_mov_b32_e32 v52, v2
	v_mov_b32_e32 v53, v2
	v_mov_b32_e32 v54, v2
	v_mov_b32_e32 v55, v2
	v_mov_b32_e32 v56, v2
	v_mov_b32_e32 v57, v2
	v_mov_b32_e32 v66, v2
	v_mov_b32_e32 v67, v2
	v_mov_b32_e32 v68, v2
	v_mov_b32_e32 v69, v2
	v_mov_b32_e32 v70, v2
	v_mov_b32_e32 v71, v2
	v_mov_b32_e32 v72, v2
	v_mov_b32_e32 v73, v2
	v_mov_b32_e32 v10, v2
	v_mov_b32_e32 v11, v2
	v_mov_b32_e32 v12, v2
	v_mov_b32_e32 v13, v2
	v_mov_b32_e32 v14, v2
	v_mov_b32_e32 v15, v2
	v_mov_b32_e32 v16, v2
	v_mov_b32_e32 v17, v2
	v_mov_b32_e32 v26, v2
	v_mov_b32_e32 v27, v2
	v_mov_b32_e32 v28, v2
	v_mov_b32_e32 v29, v2
	v_mov_b32_e32 v30, v2
	v_mov_b32_e32 v31, v2
	v_mov_b32_e32 v32, v2
	v_mov_b32_e32 v33, v2
	v_mov_b32_e32 v58, v2
	v_mov_b32_e32 v59, v2
	v_mov_b32_e32 v60, v2
	v_mov_b32_e32 v61, v2
	v_mov_b32_e32 v62, v2
	v_mov_b32_e32 v63, v2
	v_mov_b32_e32 v64, v2
	v_mov_b32_e32 v65, v2
	v_mov_b32_e32 v74, v2
	v_mov_b32_e32 v75, v2
	v_mov_b32_e32 v76, v2
	v_mov_b32_e32 v77, v2
	v_mov_b32_e32 v78, v2
	v_mov_b32_e32 v79, v2
	v_mov_b32_e32 v80, v2
	v_mov_b32_e32 v81, v2
	v_mov_b32_e32 v82, v2
	v_mov_b32_e32 v83, v2
	v_mov_b32_e32 v84, v2
	v_mov_b32_e32 v85, v2
	v_mov_b32_e32 v86, v2
	v_mov_b32_e32 v87, v2
	v_mov_b32_e32 v88, v2
	v_mov_b32_e32 v89, v2
	v_mov_b32_e32 v98, v2
	v_mov_b32_e32 v99, v2
	v_mov_b32_e32 v100, v2
	v_mov_b32_e32 v101, v2
	v_mov_b32_e32 v102, v2
	v_mov_b32_e32 v103, v2
	v_mov_b32_e32 v104, v2
	v_mov_b32_e32 v105, v2
	v_mov_b32_e32 v114, v2
	v_mov_b32_e32 v115, v2
	v_mov_b32_e32 v116, v2
	v_mov_b32_e32 v117, v2
	v_mov_b32_e32 v118, v2
	v_mov_b32_e32 v119, v2
	v_mov_b32_e32 v120, v2
	v_mov_b32_e32 v121, v2
	v_mov_b32_e32 v130, v2
	v_mov_b32_e32 v131, v2
	v_mov_b32_e32 v132, v2
	v_mov_b32_e32 v133, v2
	v_mov_b32_e32 v134, v2
	v_mov_b32_e32 v135, v2
	v_mov_b32_e32 v136, v2
	v_mov_b32_e32 v137, v2
	v_mov_b32_e32 v90, v2
	v_mov_b32_e32 v91, v2
	v_mov_b32_e32 v92, v2
	v_mov_b32_e32 v93, v2
	v_mov_b32_e32 v94, v2
	v_mov_b32_e32 v95, v2
	v_mov_b32_e32 v96, v2
	v_mov_b32_e32 v97, v2
	v_mov_b32_e32 v106, v2
	v_mov_b32_e32 v107, v2
	v_mov_b32_e32 v108, v2
	v_mov_b32_e32 v109, v2
	v_mov_b32_e32 v110, v2
	v_mov_b32_e32 v111, v2
	v_mov_b32_e32 v112, v2
	v_mov_b32_e32 v113, v2
	v_mov_b32_e32 v122, v2
	v_mov_b32_e32 v123, v2
	v_mov_b32_e32 v124, v2
	v_mov_b32_e32 v125, v2
	v_mov_b32_e32 v126, v2
	v_mov_b32_e32 v127, v2
	v_mov_b32_e32 v128, v2
	v_mov_b32_e32 v129, v2
	v_mov_b32_e32 v138, v2
	v_mov_b32_e32 v139, v2
	v_mov_b32_e32 v140, v2
	v_mov_b32_e32 v141, v2
	v_mov_b32_e32 v142, v2
	v_mov_b32_e32 v143, v2
	v_mov_b32_e32 v144, v2
	v_mov_b32_e32 v145, v2
	.p2alignl 6, 3212836864
	v_add_u32_e32 v251, 0x80, v150
	v_add_u32_e32 v252, 0x80, v154
	v_add_u32_e32 v253, 0x80, v148
	v_add_u32_e32 v254, 0x80, v152

.LBB0_632:
	s_add_i32 s81, s87, -2
	s_add_u32 s88, s88, 0x40080
	s_addc_u32 s89, s89, 0
	s_add_u32 s83, s90, 0x100
	v_mov_b32_e32 v2, 0
	s_addc_u32 vcc_lo, s91, 0
	s_mov_b32 s12, 0
	v_mov_b32_e32 v3, v2
	v_mov_b32_e32 v4, v2
	v_mov_b32_e32 v5, v2
	v_mov_b32_e32 v6, v2
	v_mov_b32_e32 v7, v2
	v_mov_b32_e32 v8, v2
	v_mov_b32_e32 v9, v2
	v_mov_b32_e32 v10, v2
	v_mov_b32_e32 v11, v2
	v_mov_b32_e32 v12, v2
	v_mov_b32_e32 v13, v2
	v_mov_b32_e32 v14, v2
	v_mov_b32_e32 v15, v2
	v_mov_b32_e32 v16, v2
	v_mov_b32_e32 v17, v2
	v_mov_b32_e32 v22, v2
	v_mov_b32_e32 v23, v2
	v_mov_b32_e32 v24, v2
	v_mov_b32_e32 v25, v2
	v_mov_b32_e32 v30, v2
	v_mov_b32_e32 v31, v2
	v_mov_b32_e32 v32, v2
	v_mov_b32_e32 v33, v2
	v_mov_b32_e32 v38, v2
	v_mov_b32_e32 v39, v2
	v_mov_b32_e32 v40, v2
	v_mov_b32_e32 v41, v2
	v_mov_b32_e32 v46, v2
	v_mov_b32_e32 v47, v2
	v_mov_b32_e32 v48, v2
	v_mov_b32_e32 v49, v2
	v_mov_b32_e32 v18, v2
	v_mov_b32_e32 v19, v2
	v_mov_b32_e32 v20, v2
	v_mov_b32_e32 v21, v2
	v_mov_b32_e32 v26, v2
	v_mov_b32_e32 v27, v2
	v_mov_b32_e32 v28, v2
	v_mov_b32_e32 v29, v2
	v_mov_b32_e32 v34, v2
	v_mov_b32_e32 v35, v2
	v_mov_b32_e32 v36, v2
	v_mov_b32_e32 v37, v2
	v_mov_b32_e32 v42, v2
	v_mov_b32_e32 v43, v2
	v_mov_b32_e32 v44, v2
	v_mov_b32_e32 v45, v2
	v_mov_b32_e32 v50, v2
	v_mov_b32_e32 v51, v2
	v_mov_b32_e32 v52, v2
	v_mov_b32_e32 v53, v2
	v_mov_b32_e32 v54, v2
	v_mov_b32_e32 v55, v2
	v_mov_b32_e32 v56, v2
	v_mov_b32_e32 v57, v2
	v_mov_b32_e32 v58, v2
	v_mov_b32_e32 v59, v2
	v_mov_b32_e32 v60, v2
	v_mov_b32_e32 v61, v2
	v_mov_b32_e32 v62, v2
	v_mov_b32_e32 v63, v2
	v_mov_b32_e32 v64, v2
	v_mov_b32_e32 v65, v2
	v_mov_b32_e32 v66, v2
	v_mov_b32_e32 v67, v2
	v_mov_b32_e32 v68, v2
	v_mov_b32_e32 v69, v2
	v_mov_b32_e32 v70, v2
	v_mov_b32_e32 v71, v2
	v_mov_b32_e32 v72, v2
	v_mov_b32_e32 v73, v2
	v_mov_b32_e32 v74, v2
	v_mov_b32_e32 v75, v2
	v_mov_b32_e32 v76, v2
	v_mov_b32_e32 v77, v2
	v_mov_b32_e32 v78, v2
	v_mov_b32_e32 v79, v2
	v_mov_b32_e32 v80, v2
	v_mov_b32_e32 v81, v2
	v_mov_b32_e32 v86, v2
	v_mov_b32_e32 v87, v2
	v_mov_b32_e32 v88, v2
	v_mov_b32_e32 v89, v2
	v_mov_b32_e32 v94, v2
	v_mov_b32_e32 v95, v2
	v_mov_b32_e32 v96, v2
	v_mov_b32_e32 v97, v2
	v_mov_b32_e32 v102, v2
	v_mov_b32_e32 v103, v2
	v_mov_b32_e32 v104, v2
	v_mov_b32_e32 v105, v2
	v_mov_b32_e32 v110, v2
	v_mov_b32_e32 v111, v2
	v_mov_b32_e32 v112, v2
	v_mov_b32_e32 v113, v2
	v_mov_b32_e32 v82, v2
	v_mov_b32_e32 v83, v2
	v_mov_b32_e32 v84, v2
	v_mov_b32_e32 v85, v2
	v_mov_b32_e32 v90, v2
	v_mov_b32_e32 v91, v2
	v_mov_b32_e32 v92, v2
	v_mov_b32_e32 v93, v2
	v_mov_b32_e32 v98, v2
	v_mov_b32_e32 v99, v2
	v_mov_b32_e32 v100, v2
	v_mov_b32_e32 v101, v2
	v_mov_b32_e32 v106, v2
	v_mov_b32_e32 v107, v2
	v_mov_b32_e32 v108, v2
	v_mov_b32_e32 v109, v2
	v_mov_b32_e32 v114, v2
	v_mov_b32_e32 v115, v2
	v_mov_b32_e32 v116, v2
	v_mov_b32_e32 v117, v2
	v_mov_b32_e32 v118, v2
	v_mov_b32_e32 v119, v2
	v_mov_b32_e32 v120, v2
	v_mov_b32_e32 v121, v2
	v_mov_b32_e32 v122, v2
	v_mov_b32_e32 v123, v2
	v_mov_b32_e32 v124, v2
	v_mov_b32_e32 v125, v2
	v_mov_b32_e32 v126, v2
	v_mov_b32_e32 v127, v2
	v_mov_b32_e32 v128, v2
	v_mov_b32_e32 v129, v2
	.p2alignl 6, 3212836864
	v_add_u32_e32 v251, 0x80, v134
	v_add_u32_e32 v252, 0x80, v130
	v_add_u32_e32 v253, 0x80, v136
	v_add_u32_e32 v254, 0x80, v132

.LBB0_662:
	s_ashr_i32 s73, s72, 31
	s_lshl_b64 s[12:13], s[72:73], 19
	v_cmp_lt_i64_e32 vcc, s[74:75], v[150:151]
	s_add_u32 s74, s19, s12
	s_addc_u32 s75, s27, s13
	s_and_b64 s[12:13], vcc, exec
	s_cselect_b32 s37, s75, s83
	s_cselect_b32 s49, s74, s82
	s_ashr_i32 s71, s70, 31
	s_lshl_b64 s[12:13], s[70:71], 19
	s_add_u32 s76, s66, s12
	s_addc_u32 s77, s67, s13
	s_and_b64 s[12:13], vcc, exec
	s_cselect_b32 s71, s77, s85
	s_cselect_b32 s73, s76, s84
	s_add_u32 s82, s82, 0x40080
	s_addc_u32 s83, s83, 0
	s_add_u32 s79, s84, 0x100
	v_mov_b32_e32 v2, 0
	s_addc_u32 vcc_lo, s85, 0
	s_mov_b32 s12, -2
	s_waitcnt lgkmcnt(0)
	v_mov_b32_e32 v3, v2
	v_mov_b32_e32 v4, v2
	v_mov_b32_e32 v5, v2
	v_mov_b32_e32 v6, v2
	v_mov_b32_e32 v7, v2
	v_mov_b32_e32 v8, v2
	v_mov_b32_e32 v9, v2
	v_mov_b32_e32 v10, v2
	v_mov_b32_e32 v11, v2
	v_mov_b32_e32 v12, v2
	v_mov_b32_e32 v13, v2
	v_mov_b32_e32 v14, v2
	v_mov_b32_e32 v15, v2
	v_mov_b32_e32 v16, v2
	v_mov_b32_e32 v17, v2
	v_mov_b32_e32 v18, v2
	v_mov_b32_e32 v19, v2
	v_mov_b32_e32 v20, v2
	v_mov_b32_e32 v21, v2
	v_mov_b32_e32 v22, v2
	v_mov_b32_e32 v23, v2
	v_mov_b32_e32 v24, v2
	v_mov_b32_e32 v25, v2
	v_mov_b32_e32 v26, v2
	v_mov_b32_e32 v27, v2
	v_mov_b32_e32 v28, v2
	v_mov_b32_e32 v29, v2
	v_mov_b32_e32 v30, v2
	v_mov_b32_e32 v31, v2
	v_mov_b32_e32 v32, v2
	v_mov_b32_e32 v33, v2
	v_mov_b32_e32 v66, v2
	v_mov_b32_e32 v67, v2
	v_mov_b32_e32 v68, v2
	v_mov_b32_e32 v69, v2
	v_mov_b32_e32 v70, v2
	v_mov_b32_e32 v71, v2
	v_mov_b32_e32 v72, v2
	v_mov_b32_e32 v73, v2
	v_mov_b32_e32 v74, v2
	v_mov_b32_e32 v75, v2
	v_mov_b32_e32 v76, v2
	v_mov_b32_e32 v77, v2
	v_mov_b32_e32 v78, v2
	v_mov_b32_e32 v79, v2
	v_mov_b32_e32 v80, v2
	v_mov_b32_e32 v81, v2
	v_mov_b32_e32 v82, v2
	v_mov_b32_e32 v83, v2
	v_mov_b32_e32 v84, v2
	v_mov_b32_e32 v85, v2
	v_mov_b32_e32 v86, v2
	v_mov_b32_e32 v87, v2
	v_mov_b32_e32 v88, v2
	v_mov_b32_e32 v89, v2
	v_mov_b32_e32 v90, v2
	v_mov_b32_e32 v91, v2
	v_mov_b32_e32 v92, v2
	v_mov_b32_e32 v93, v2
	v_mov_b32_e32 v94, v2
	v_mov_b32_e32 v95, v2
	v_mov_b32_e32 v96, v2
	v_mov_b32_e32 v97, v2
	v_mov_b32_e32 v34, v2
	v_mov_b32_e32 v35, v2
	v_mov_b32_e32 v36, v2
	v_mov_b32_e32 v37, v2
	v_mov_b32_e32 v38, v2
	v_mov_b32_e32 v39, v2
	v_mov_b32_e32 v40, v2
	v_mov_b32_e32 v41, v2
	v_mov_b32_e32 v42, v2
	v_mov_b32_e32 v43, v2
	v_mov_b32_e32 v44, v2
	v_mov_b32_e32 v45, v2
	v_mov_b32_e32 v46, v2
	v_mov_b32_e32 v47, v2
	v_mov_b32_e32 v48, v2
	v_mov_b32_e32 v49, v2
	v_mov_b32_e32 v50, v2
	v_mov_b32_e32 v51, v2
	v_mov_b32_e32 v52, v2
	v_mov_b32_e32 v53, v2
	v_mov_b32_e32 v54, v2
	v_mov_b32_e32 v55, v2
	v_mov_b32_e32 v56, v2
	v_mov_b32_e32 v57, v2
	v_mov_b32_e32 v58, v2
	v_mov_b32_e32 v59, v2
	v_mov_b32_e32 v60, v2
	v_mov_b32_e32 v61, v2
	v_mov_b32_e32 v62, v2
	v_mov_b32_e32 v63, v2
	v_mov_b32_e32 v64, v2
	v_mov_b32_e32 v65, v2
	v_mov_b32_e32 v106, v2
	v_mov_b32_e32 v107, v2
	v_mov_b32_e32 v108, v2
	v_mov_b32_e32 v109, v2
	v_mov_b32_e32 v110, v2
	v_mov_b32_e32 v111, v2
	v_mov_b32_e32 v112, v2
	v_mov_b32_e32 v113, v2
	v_mov_b32_e32 v114, v2
	v_mov_b32_e32 v115, v2
	v_mov_b32_e32 v116, v2
	v_mov_b32_e32 v117, v2
	v_mov_b32_e32 v118, v2
	v_mov_b32_e32 v119, v2
	v_mov_b32_e32 v120, v2
	v_mov_b32_e32 v121, v2
	v_mov_b32_e32 v122, v2
	v_mov_b32_e32 v123, v2
	v_mov_b32_e32 v124, v2
	v_mov_b32_e32 v125, v2
	v_mov_b32_e32 v126, v2
	v_mov_b32_e32 v127, v2
	v_mov_b32_e32 v128, v2
	v_mov_b32_e32 v129, v2
	v_mov_b32_e32 v130, v2
	v_mov_b32_e32 v131, v2
	v_mov_b32_e32 v132, v2
	v_mov_b32_e32 v133, v2
	v_mov_b32_e32 v134, v2
	v_mov_b32_e32 v135, v2
	v_mov_b32_e32 v136, v2
	v_mov_b32_e32 v137, v2
	.p2alignl 6, 3212836864
	v_add_u32_e32 v251, 0x80, v140
	v_add_u32_e32 v252, 0x80, v144
	v_add_u32_e32 v253, 0x80, v138
	v_add_u32_e32 v254, 0x80, v142

.LBB0_776:
	s_ashr_i32 s75, s74, 31
	s_lshl_b64 s[12:13], s[74:75], 19
	s_add_u32 s80, s4, s12
	s_addc_u32 s81, s5, s13
	s_and_b64 s[12:13], s[78:79], exec
	s_cselect_b32 s11, s81, s85
	s_cselect_b32 s37, s80, s84
	s_ashr_i32 s77, s76, 31
	s_lshl_b64 s[12:13], s[76:77], 19
	s_add_u32 s82, s19, s12
	s_addc_u32 s83, s22, s13
	s_and_b64 s[12:13], s[78:79], exec
	s_cselect_b32 s75, s83, s87
	s_cselect_b32 s77, s82, s86
	s_add_u32 s84, s84, 0x40080
	s_addc_u32 s85, s85, 0
	s_add_u32 s92, s86, 0x100
	v_mov_b32_e32 v2, 0
	s_addc_u32 s93, s87, 0
	s_mov_b32 s12, -2
	v_mov_b32_e32 v3, v2
	v_mov_b32_e32 v4, v2
	v_mov_b32_e32 v5, v2
	v_mov_b32_e32 v6, v2
	v_mov_b32_e32 v7, v2
	v_mov_b32_e32 v8, v2
	v_mov_b32_e32 v9, v2
	v_mov_b32_e32 v18, v2
	v_mov_b32_e32 v19, v2
	v_mov_b32_e32 v20, v2
	v_mov_b32_e32 v21, v2
	v_mov_b32_e32 v22, v2
	v_mov_b32_e32 v23, v2
	v_mov_b32_e32 v24, v2
	v_mov_b32_e32 v25, v2
	v_mov_b32_e32 v34, v2
	v_mov_b32_e32 v35, v2
	v_mov_b32_e32 v36, v2
	v_mov_b32_e32 v37, v2
	v_mov_b32_e32 v38, v2
	v_mov_b32_e32 v39, v2
	v_mov_b32_e32 v40, v2
	v_mov_b32_e32 v41, v2
	v_mov_b32_e32 v66, v2
	v_mov_b32_e32 v67, v2
	v_mov_b32_e32 v68, v2
	v_mov_b32_e32 v69, v2
	v_mov_b32_e32 v70, v2
	v_mov_b32_e32 v71, v2
	v_mov_b32_e32 v72, v2
	v_mov_b32_e32 v73, v2
	v_mov_b32_e32 v10, v2
	v_mov_b32_e32 v11, v2
	v_mov_b32_e32 v12, v2
	v_mov_b32_e32 v13, v2
	v_mov_b32_e32 v14, v2
	v_mov_b32_e32 v15, v2
	v_mov_b32_e32 v16, v2
	v_mov_b32_e32 v17, v2
	v_mov_b32_e32 v26, v2
	v_mov_b32_e32 v27, v2
	v_mov_b32_e32 v28, v2
	v_mov_b32_e32 v29, v2
	v_mov_b32_e32 v30, v2
	v_mov_b32_e32 v31, v2
	v_mov_b32_e32 v32, v2
	v_mov_b32_e32 v33, v2
	v_mov_b32_e32 v42, v2
	v_mov_b32_e32 v43, v2
	v_mov_b32_e32 v44, v2
	v_mov_b32_e32 v45, v2
	v_mov_b32_e32 v46, v2
	v_mov_b32_e32 v47, v2
	v_mov_b32_e32 v48, v2
	v_mov_b32_e32 v49, v2
	v_mov_b32_e32 v74, v2
	v_mov_b32_e32 v75, v2
	v_mov_b32_e32 v76, v2
	v_mov_b32_e32 v77, v2
	v_mov_b32_e32 v78, v2
	v_mov_b32_e32 v79, v2
	v_mov_b32_e32 v80, v2
	v_mov_b32_e32 v81, v2
	v_mov_b32_e32 v82, v2
	v_mov_b32_e32 v83, v2
	v_mov_b32_e32 v84, v2
	v_mov_b32_e32 v85, v2
	v_mov_b32_e32 v86, v2
	v_mov_b32_e32 v87, v2
	v_mov_b32_e32 v88, v2
	v_mov_b32_e32 v89, v2
	v_mov_b32_e32 v98, v2
	v_mov_b32_e32 v99, v2
	v_mov_b32_e32 v100, v2
	v_mov_b32_e32 v101, v2
	v_mov_b32_e32 v102, v2
	v_mov_b32_e32 v103, v2
	v_mov_b32_e32 v104, v2
	v_mov_b32_e32 v105, v2
	v_mov_b32_e32 v114, v2
	v_mov_b32_e32 v115, v2
	v_mov_b32_e32 v116, v2
	v_mov_b32_e32 v117, v2
	v_mov_b32_e32 v118, v2
	v_mov_b32_e32 v119, v2
	v_mov_b32_e32 v120, v2
	v_mov_b32_e32 v121, v2
	v_mov_b32_e32 v130, v2
	v_mov_b32_e32 v131, v2
	v_mov_b32_e32 v132, v2
	v_mov_b32_e32 v133, v2
	v_mov_b32_e32 v134, v2
	v_mov_b32_e32 v135, v2
	v_mov_b32_e32 v136, v2
	v_mov_b32_e32 v137, v2
	v_mov_b32_e32 v90, v2
	v_mov_b32_e32 v91, v2
	v_mov_b32_e32 v92, v2
	v_mov_b32_e32 v93, v2
	v_mov_b32_e32 v94, v2
	v_mov_b32_e32 v95, v2
	v_mov_b32_e32 v96, v2
	v_mov_b32_e32 v97, v2
	v_mov_b32_e32 v106, v2
	v_mov_b32_e32 v107, v2
	v_mov_b32_e32 v108, v2
	v_mov_b32_e32 v109, v2
	v_mov_b32_e32 v110, v2
	v_mov_b32_e32 v111, v2
	v_mov_b32_e32 v112, v2
	v_mov_b32_e32 v113, v2
	v_mov_b32_e32 v122, v2
	v_mov_b32_e32 v123, v2
	v_mov_b32_e32 v124, v2
	v_mov_b32_e32 v125, v2
	v_mov_b32_e32 v126, v2
	v_mov_b32_e32 v127, v2
	v_mov_b32_e32 v128, v2
	v_mov_b32_e32 v129, v2
	v_mov_b32_e32 v138, v2
	v_mov_b32_e32 v139, v2
	v_mov_b32_e32 v140, v2
	v_mov_b32_e32 v141, v2
	v_mov_b32_e32 v142, v2
	v_mov_b32_e32 v143, v2
	v_mov_b32_e32 v144, v2
	v_mov_b32_e32 v145, v2
	.p2alignl 6, 3212836864
	v_add_u32_e32 v251, 0x80, v150
	v_add_u32_e32 v252, 0x80, v154
	v_add_u32_e32 v253, 0x80, v148
	v_add_u32_e32 v254, 0x80, v152

.LBB0_817:
	s_add_i32 s80, s21, -2
	s_add_u32 s81, s70, 0x100
	v_mov_b32_e32 v2, 0
	s_addc_u32 s82, s71, 0
	s_mov_b32 s12, 0
	v_mov_b32_e32 v3, v2
	v_mov_b32_e32 v4, v2
	v_mov_b32_e32 v5, v2
	v_mov_b32_e32 v6, v2
	v_mov_b32_e32 v7, v2
	v_mov_b32_e32 v8, v2
	v_mov_b32_e32 v9, v2
	v_mov_b32_e32 v10, v2
	v_mov_b32_e32 v11, v2
	v_mov_b32_e32 v12, v2
	v_mov_b32_e32 v13, v2
	v_mov_b32_e32 v14, v2
	v_mov_b32_e32 v15, v2
	v_mov_b32_e32 v16, v2
	v_mov_b32_e32 v17, v2
	v_mov_b32_e32 v18, v2
	v_mov_b32_e32 v19, v2
	v_mov_b32_e32 v20, v2
	v_mov_b32_e32 v21, v2
	v_mov_b32_e32 v26, v2
	v_mov_b32_e32 v27, v2
	v_mov_b32_e32 v28, v2
	v_mov_b32_e32 v29, v2
	v_mov_b32_e32 v34, v2
	v_mov_b32_e32 v35, v2
	v_mov_b32_e32 v36, v2
	v_mov_b32_e32 v37, v2
	v_mov_b32_e32 v42, v2
	v_mov_b32_e32 v43, v2
	v_mov_b32_e32 v44, v2
	v_mov_b32_e32 v45, v2
	v_mov_b32_e32 v22, v2
	v_mov_b32_e32 v23, v2
	v_mov_b32_e32 v24, v2
	v_mov_b32_e32 v25, v2
	v_mov_b32_e32 v30, v2
	v_mov_b32_e32 v31, v2
	v_mov_b32_e32 v32, v2
	v_mov_b32_e32 v33, v2
	v_mov_b32_e32 v38, v2
	v_mov_b32_e32 v39, v2
	v_mov_b32_e32 v40, v2
	v_mov_b32_e32 v41, v2
	v_mov_b32_e32 v46, v2
	v_mov_b32_e32 v47, v2
	v_mov_b32_e32 v48, v2
	v_mov_b32_e32 v49, v2
	v_mov_b32_e32 v50, v2
	v_mov_b32_e32 v51, v2
	v_mov_b32_e32 v52, v2
	v_mov_b32_e32 v53, v2
	v_mov_b32_e32 v54, v2
	v_mov_b32_e32 v55, v2
	v_mov_b32_e32 v56, v2
	v_mov_b32_e32 v57, v2
	v_mov_b32_e32 v58, v2
	v_mov_b32_e32 v59, v2
	v_mov_b32_e32 v60, v2
	v_mov_b32_e32 v61, v2
	v_mov_b32_e32 v62, v2
	v_mov_b32_e32 v63, v2
	v_mov_b32_e32 v64, v2
	v_mov_b32_e32 v65, v2
	v_mov_b32_e32 v66, v2
	v_mov_b32_e32 v67, v2
	v_mov_b32_e32 v68, v2
	v_mov_b32_e32 v69, v2
	v_mov_b32_e32 v70, v2
	v_mov_b32_e32 v71, v2
	v_mov_b32_e32 v72, v2
	v_mov_b32_e32 v73, v2
	v_mov_b32_e32 v74, v2
	v_mov_b32_e32 v75, v2
	v_mov_b32_e32 v76, v2
	v_mov_b32_e32 v77, v2
	v_mov_b32_e32 v78, v2
	v_mov_b32_e32 v79, v2
	v_mov_b32_e32 v80, v2
	v_mov_b32_e32 v81, v2
	v_mov_b32_e32 v82, v2
	v_mov_b32_e32 v83, v2
	v_mov_b32_e32 v84, v2
	v_mov_b32_e32 v85, v2
	v_mov_b32_e32 v90, v2
	v_mov_b32_e32 v91, v2
	v_mov_b32_e32 v92, v2
	v_mov_b32_e32 v93, v2
	v_mov_b32_e32 v98, v2
	v_mov_b32_e32 v99, v2
	v_mov_b32_e32 v100, v2
	v_mov_b32_e32 v101, v2
	v_mov_b32_e32 v106, v2
	v_mov_b32_e32 v107, v2
	v_mov_b32_e32 v108, v2
	v_mov_b32_e32 v109, v2
	v_mov_b32_e32 v86, v2
	v_mov_b32_e32 v87, v2
	v_mov_b32_e32 v88, v2
	v_mov_b32_e32 v89, v2
	v_mov_b32_e32 v94, v2
	v_mov_b32_e32 v95, v2
	v_mov_b32_e32 v96, v2
	v_mov_b32_e32 v97, v2
	v_mov_b32_e32 v102, v2
	v_mov_b32_e32 v103, v2
	v_mov_b32_e32 v104, v2
	v_mov_b32_e32 v105, v2
	v_mov_b32_e32 v110, v2
	v_mov_b32_e32 v111, v2
	v_mov_b32_e32 v112, v2
	v_mov_b32_e32 v113, v2
	v_mov_b32_e32 v114, v2
	v_mov_b32_e32 v115, v2
	v_mov_b32_e32 v116, v2
	v_mov_b32_e32 v117, v2
	v_mov_b32_e32 v118, v2
	v_mov_b32_e32 v119, v2
	v_mov_b32_e32 v120, v2
	v_mov_b32_e32 v121, v2
	v_mov_b32_e32 v122, v2
	v_mov_b32_e32 v123, v2
	v_mov_b32_e32 v124, v2
	v_mov_b32_e32 v125, v2
	v_mov_b32_e32 v126, v2
	v_mov_b32_e32 v127, v2
	v_mov_b32_e32 v128, v2
	v_mov_b32_e32 v129, v2
	.p2alignl 6, 3212836864
	v_add_u32_e32 v251, 0x80, v134
	v_add_u32_e32 v252, 0x80, v130
	v_add_u32_e32 v253, 0x80, v136
	v_add_u32_e32 v254, 0x80, v132

.LBB0_903:
	s_add_u32 s69, s72, 0x100
	v_mov_b32_e32 v2, 0
	s_addc_u32 s87, s73, 0
	s_mov_b32 s12, -2
	s_waitcnt lgkmcnt(0)
	v_mov_b32_e32 v3, v2
	v_mov_b32_e32 v4, v2
	v_mov_b32_e32 v5, v2
	v_mov_b32_e32 v6, v2
	v_mov_b32_e32 v7, v2
	v_mov_b32_e32 v8, v2
	v_mov_b32_e32 v9, v2
	v_mov_b32_e32 v10, v2
	v_mov_b32_e32 v11, v2
	v_mov_b32_e32 v12, v2
	v_mov_b32_e32 v13, v2
	v_mov_b32_e32 v14, v2
	v_mov_b32_e32 v15, v2
	v_mov_b32_e32 v16, v2
	v_mov_b32_e32 v17, v2
	v_mov_b32_e32 v18, v2
	v_mov_b32_e32 v19, v2
	v_mov_b32_e32 v20, v2
	v_mov_b32_e32 v21, v2
	v_mov_b32_e32 v22, v2
	v_mov_b32_e32 v23, v2
	v_mov_b32_e32 v24, v2
	v_mov_b32_e32 v25, v2
	v_mov_b32_e32 v26, v2
	v_mov_b32_e32 v27, v2
	v_mov_b32_e32 v28, v2
	v_mov_b32_e32 v29, v2
	v_mov_b32_e32 v30, v2
	v_mov_b32_e32 v31, v2
	v_mov_b32_e32 v32, v2
	v_mov_b32_e32 v33, v2
	v_mov_b32_e32 v66, v2
	v_mov_b32_e32 v67, v2
	v_mov_b32_e32 v68, v2
	v_mov_b32_e32 v69, v2
	v_mov_b32_e32 v70, v2
	v_mov_b32_e32 v71, v2
	v_mov_b32_e32 v72, v2
	v_mov_b32_e32 v73, v2
	v_mov_b32_e32 v74, v2
	v_mov_b32_e32 v75, v2
	v_mov_b32_e32 v76, v2
	v_mov_b32_e32 v77, v2
	v_mov_b32_e32 v78, v2
	v_mov_b32_e32 v79, v2
	v_mov_b32_e32 v80, v2
	v_mov_b32_e32 v81, v2
	v_mov_b32_e32 v82, v2
	v_mov_b32_e32 v83, v2
	v_mov_b32_e32 v84, v2
	v_mov_b32_e32 v85, v2
	v_mov_b32_e32 v86, v2
	v_mov_b32_e32 v87, v2
	v_mov_b32_e32 v88, v2
	v_mov_b32_e32 v89, v2
	v_mov_b32_e32 v90, v2
	v_mov_b32_e32 v91, v2
	v_mov_b32_e32 v92, v2
	v_mov_b32_e32 v93, v2
	v_mov_b32_e32 v94, v2
	v_mov_b32_e32 v95, v2
	v_mov_b32_e32 v96, v2
	v_mov_b32_e32 v97, v2
	v_mov_b32_e32 v34, v2
	v_mov_b32_e32 v35, v2
	v_mov_b32_e32 v36, v2
	v_mov_b32_e32 v37, v2
	v_mov_b32_e32 v38, v2
	v_mov_b32_e32 v39, v2
	v_mov_b32_e32 v40, v2
	v_mov_b32_e32 v41, v2
	v_mov_b32_e32 v42, v2
	v_mov_b32_e32 v43, v2
	v_mov_b32_e32 v44, v2
	v_mov_b32_e32 v45, v2
	v_mov_b32_e32 v46, v2
	v_mov_b32_e32 v47, v2
	v_mov_b32_e32 v48, v2
	v_mov_b32_e32 v49, v2
	v_mov_b32_e32 v50, v2
	v_mov_b32_e32 v51, v2
	v_mov_b32_e32 v52, v2
	v_mov_b32_e32 v53, v2
	v_mov_b32_e32 v54, v2
	v_mov_b32_e32 v55, v2
	v_mov_b32_e32 v56, v2
	v_mov_b32_e32 v57, v2
	v_mov_b32_e32 v58, v2
	v_mov_b32_e32 v59, v2
	v_mov_b32_e32 v60, v2
	v_mov_b32_e32 v61, v2
	v_mov_b32_e32 v62, v2
	v_mov_b32_e32 v63, v2
	v_mov_b32_e32 v64, v2
	v_mov_b32_e32 v65, v2
	v_mov_b32_e32 v98, v2
	v_mov_b32_e32 v99, v2
	v_mov_b32_e32 v100, v2
	v_mov_b32_e32 v101, v2
	v_mov_b32_e32 v102, v2
	v_mov_b32_e32 v103, v2
	v_mov_b32_e32 v104, v2
	v_mov_b32_e32 v105, v2
	v_mov_b32_e32 v106, v2
	v_mov_b32_e32 v107, v2
	v_mov_b32_e32 v108, v2
	v_mov_b32_e32 v109, v2
	v_mov_b32_e32 v110, v2
	v_mov_b32_e32 v111, v2
	v_mov_b32_e32 v112, v2
	v_mov_b32_e32 v113, v2
	v_mov_b32_e32 v114, v2
	v_mov_b32_e32 v115, v2
	v_mov_b32_e32 v116, v2
	v_mov_b32_e32 v117, v2
	v_mov_b32_e32 v118, v2
	v_mov_b32_e32 v119, v2
	v_mov_b32_e32 v120, v2
	v_mov_b32_e32 v121, v2
	v_mov_b32_e32 v122, v2
	v_mov_b32_e32 v123, v2
	v_mov_b32_e32 v124, v2
	v_mov_b32_e32 v125, v2
	v_mov_b32_e32 v126, v2
	v_mov_b32_e32 v127, v2
	v_mov_b32_e32 v128, v2
	v_mov_b32_e32 v129, v2
	.p2alignl 6, 3212836864
	v_add_u32_e32 v251, 0x80, v140
	v_add_u32_e32 v252, 0x80, v144
	v_add_u32_e32 v253, 0x80, v138
	v_add_u32_e32 v254, 0x80, v142

.LBB0_990:
	s_ashr_i32 s79, s78, 31
	s_lshl_b64 s[12:13], s[78:79], 19
	s_add_u32 s80, s19, s12
	s_addc_u32 s81, s27, s13
	s_and_b64 s[12:13], s[6:7], exec
	s_cselect_b32 s11, s81, s1
	s_cselect_b32 s23, s80, s0
	s_ashr_i32 s77, s76, 31
	s_lshl_b64 s[12:13], s[76:77], 19
	s_add_u32 s82, s36, s12
	s_addc_u32 s83, s37, s13
	s_and_b64 s[12:13], s[6:7], exec
	s_cselect_b32 s48, s83, s85
	s_cselect_b32 s49, s82, s84
	s_add_u32 s0, s0, 0x40080
	s_addc_u32 s1, s1, 0
	s_add_u32 s63, s84, 0x100
	v_mov_b32_e32 v2, 0
	s_addc_u32 s77, s85, 0
	s_mov_b32 s12, -2
	v_mov_b32_e32 v3, v2
	v_mov_b32_e32 v4, v2
	v_mov_b32_e32 v5, v2
	v_mov_b32_e32 v6, v2
	v_mov_b32_e32 v7, v2
	v_mov_b32_e32 v8, v2
	v_mov_b32_e32 v9, v2
	v_mov_b32_e32 v18, v2
	v_mov_b32_e32 v19, v2
	v_mov_b32_e32 v20, v2
	v_mov_b32_e32 v21, v2
	v_mov_b32_e32 v22, v2
	v_mov_b32_e32 v23, v2
	v_mov_b32_e32 v24, v2
	v_mov_b32_e32 v25, v2
	v_mov_b32_e32 v50, v2
	v_mov_b32_e32 v51, v2
	v_mov_b32_e32 v52, v2
	v_mov_b32_e32 v53, v2
	v_mov_b32_e32 v54, v2
	v_mov_b32_e32 v55, v2
	v_mov_b32_e32 v56, v2
	v_mov_b32_e32 v57, v2
	v_mov_b32_e32 v66, v2
	v_mov_b32_e32 v67, v2
	v_mov_b32_e32 v68, v2
	v_mov_b32_e32 v69, v2
	v_mov_b32_e32 v70, v2
	v_mov_b32_e32 v71, v2
	v_mov_b32_e32 v72, v2
	v_mov_b32_e32 v73, v2
	v_mov_b32_e32 v10, v2
	v_mov_b32_e32 v11, v2
	v_mov_b32_e32 v12, v2
	v_mov_b32_e32 v13, v2
	v_mov_b32_e32 v14, v2
	v_mov_b32_e32 v15, v2
	v_mov_b32_e32 v16, v2
	v_mov_b32_e32 v17, v2
	v_mov_b32_e32 v26, v2
	v_mov_b32_e32 v27, v2
	v_mov_b32_e32 v28, v2
	v_mov_b32_e32 v29, v2
	v_mov_b32_e32 v30, v2
	v_mov_b32_e32 v31, v2
	v_mov_b32_e32 v32, v2
	v_mov_b32_e32 v33, v2
	v_mov_b32_e32 v58, v2
	v_mov_b32_e32 v59, v2
	v_mov_b32_e32 v60, v2
	v_mov_b32_e32 v61, v2
	v_mov_b32_e32 v62, v2
	v_mov_b32_e32 v63, v2
	v_mov_b32_e32 v64, v2
	v_mov_b32_e32 v65, v2
	v_mov_b32_e32 v74, v2
	v_mov_b32_e32 v75, v2
	v_mov_b32_e32 v76, v2
	v_mov_b32_e32 v77, v2
	v_mov_b32_e32 v78, v2
	v_mov_b32_e32 v79, v2
	v_mov_b32_e32 v80, v2
	v_mov_b32_e32 v81, v2
	v_mov_b32_e32 v82, v2
	v_mov_b32_e32 v83, v2
	v_mov_b32_e32 v84, v2
	v_mov_b32_e32 v85, v2
	v_mov_b32_e32 v86, v2
	v_mov_b32_e32 v87, v2
	v_mov_b32_e32 v88, v2
	v_mov_b32_e32 v89, v2
	v_mov_b32_e32 v98, v2
	v_mov_b32_e32 v99, v2
	v_mov_b32_e32 v100, v2
	v_mov_b32_e32 v101, v2
	v_mov_b32_e32 v102, v2
	v_mov_b32_e32 v103, v2
	v_mov_b32_e32 v104, v2
	v_mov_b32_e32 v105, v2
	v_mov_b32_e32 v114, v2
	v_mov_b32_e32 v115, v2
	v_mov_b32_e32 v116, v2
	v_mov_b32_e32 v117, v2
	v_mov_b32_e32 v118, v2
	v_mov_b32_e32 v119, v2
	v_mov_b32_e32 v120, v2
	v_mov_b32_e32 v121, v2
	v_mov_b32_e32 v130, v2
	v_mov_b32_e32 v131, v2
	v_mov_b32_e32 v132, v2
	v_mov_b32_e32 v133, v2
	v_mov_b32_e32 v134, v2
	v_mov_b32_e32 v135, v2
	v_mov_b32_e32 v136, v2
	v_mov_b32_e32 v137, v2
	v_mov_b32_e32 v90, v2
	v_mov_b32_e32 v91, v2
	v_mov_b32_e32 v92, v2
	v_mov_b32_e32 v93, v2
	v_mov_b32_e32 v94, v2
	v_mov_b32_e32 v95, v2
	v_mov_b32_e32 v96, v2
	v_mov_b32_e32 v97, v2
	v_mov_b32_e32 v106, v2
	v_mov_b32_e32 v107, v2
	v_mov_b32_e32 v108, v2
	v_mov_b32_e32 v109, v2
	v_mov_b32_e32 v110, v2
	v_mov_b32_e32 v111, v2
	v_mov_b32_e32 v112, v2
	v_mov_b32_e32 v113, v2
	v_mov_b32_e32 v122, v2
	v_mov_b32_e32 v123, v2
	v_mov_b32_e32 v124, v2
	v_mov_b32_e32 v125, v2
	v_mov_b32_e32 v126, v2
	v_mov_b32_e32 v127, v2
	v_mov_b32_e32 v128, v2
	v_mov_b32_e32 v129, v2
	v_mov_b32_e32 v138, v2
	v_mov_b32_e32 v139, v2
	v_mov_b32_e32 v140, v2
	v_mov_b32_e32 v141, v2
	v_mov_b32_e32 v142, v2
	v_mov_b32_e32 v143, v2
	v_mov_b32_e32 v144, v2
	v_mov_b32_e32 v145, v2
	.p2alignl 6, 3212836864
	v_add_u32_e32 v251, 0x80, v150
	v_add_u32_e32 v252, 0x80, v154
	v_add_u32_e32 v253, 0x80, v148
	v_add_u32_e32 v254, 0x80, v152

.LBB0_1393:
	s_ashr_i32 s25, s24, 31
	s_lshl_b64 s[12:13], s[24:25], 19
	v_cmp_lt_i64_e32 vcc, s[26:27], v[150:151]
	s_add_u32 s26, s19, s12
	s_addc_u32 s27, s33, s13
	s_and_b64 s[12:13], vcc, exec
	s_cselect_b32 s25, s27, s43
	s_cselect_b32 s37, s26, s42
	s_ashr_i32 s23, s22, 31
	s_lshl_b64 s[12:13], s[22:23], 19
	s_add_u32 s28, s44, s12
	s_addc_u32 s29, s45, s13
	s_and_b64 s[12:13], vcc, exec
	s_cselect_b32 s23, s29, s41
	s_cselect_b32 s67, s28, s40
	s_add_u32 s30, s42, 0x40080
	s_addc_u32 s31, s43, 0
	s_add_u32 s68, s40, 0x100
	v_mov_b32_e32 v2, 0
	s_addc_u32 s69, s41, 0
	s_mov_b32 s12, -2
	s_waitcnt lgkmcnt(0)
	v_mov_b32_e32 v3, v2
	v_mov_b32_e32 v4, v2
	v_mov_b32_e32 v5, v2
	v_mov_b32_e32 v6, v2
	v_mov_b32_e32 v7, v2
	v_mov_b32_e32 v8, v2
	v_mov_b32_e32 v9, v2
	v_mov_b32_e32 v10, v2
	v_mov_b32_e32 v11, v2
	v_mov_b32_e32 v12, v2
	v_mov_b32_e32 v13, v2
	v_mov_b32_e32 v14, v2
	v_mov_b32_e32 v15, v2
	v_mov_b32_e32 v16, v2
	v_mov_b32_e32 v17, v2
	v_mov_b32_e32 v18, v2
	v_mov_b32_e32 v19, v2
	v_mov_b32_e32 v20, v2
	v_mov_b32_e32 v21, v2
	v_mov_b32_e32 v22, v2
	v_mov_b32_e32 v23, v2
	v_mov_b32_e32 v24, v2
	v_mov_b32_e32 v25, v2
	v_mov_b32_e32 v26, v2
	v_mov_b32_e32 v27, v2
	v_mov_b32_e32 v28, v2
	v_mov_b32_e32 v29, v2
	v_mov_b32_e32 v30, v2
	v_mov_b32_e32 v31, v2
	v_mov_b32_e32 v32, v2
	v_mov_b32_e32 v33, v2
	v_mov_b32_e32 v66, v2
	v_mov_b32_e32 v67, v2
	v_mov_b32_e32 v68, v2
	v_mov_b32_e32 v69, v2
	v_mov_b32_e32 v70, v2
	v_mov_b32_e32 v71, v2
	v_mov_b32_e32 v72, v2
	v_mov_b32_e32 v73, v2
	v_mov_b32_e32 v74, v2
	v_mov_b32_e32 v75, v2
	v_mov_b32_e32 v76, v2
	v_mov_b32_e32 v77, v2
	v_mov_b32_e32 v78, v2
	v_mov_b32_e32 v79, v2
	v_mov_b32_e32 v80, v2
	v_mov_b32_e32 v81, v2
	v_mov_b32_e32 v82, v2
	v_mov_b32_e32 v83, v2
	v_mov_b32_e32 v84, v2
	v_mov_b32_e32 v85, v2
	v_mov_b32_e32 v86, v2
	v_mov_b32_e32 v87, v2
	v_mov_b32_e32 v88, v2
	v_mov_b32_e32 v89, v2
	v_mov_b32_e32 v90, v2
	v_mov_b32_e32 v91, v2
	v_mov_b32_e32 v92, v2
	v_mov_b32_e32 v93, v2
	v_mov_b32_e32 v94, v2
	v_mov_b32_e32 v95, v2
	v_mov_b32_e32 v96, v2
	v_mov_b32_e32 v97, v2
	v_mov_b32_e32 v34, v2
	v_mov_b32_e32 v35, v2
	v_mov_b32_e32 v36, v2
	v_mov_b32_e32 v37, v2
	v_mov_b32_e32 v38, v2
	v_mov_b32_e32 v39, v2
	v_mov_b32_e32 v40, v2
	v_mov_b32_e32 v41, v2
	v_mov_b32_e32 v42, v2
	v_mov_b32_e32 v43, v2
	v_mov_b32_e32 v44, v2
	v_mov_b32_e32 v45, v2
	v_mov_b32_e32 v46, v2
	v_mov_b32_e32 v47, v2
	v_mov_b32_e32 v48, v2
	v_mov_b32_e32 v49, v2
	v_mov_b32_e32 v50, v2
	v_mov_b32_e32 v51, v2
	v_mov_b32_e32 v52, v2
	v_mov_b32_e32 v53, v2
	v_mov_b32_e32 v54, v2
	v_mov_b32_e32 v55, v2
	v_mov_b32_e32 v56, v2
	v_mov_b32_e32 v57, v2
	v_mov_b32_e32 v58, v2
	v_mov_b32_e32 v59, v2
	v_mov_b32_e32 v60, v2
	v_mov_b32_e32 v61, v2
	v_mov_b32_e32 v62, v2
	v_mov_b32_e32 v63, v2
	v_mov_b32_e32 v64, v2
	v_mov_b32_e32 v65, v2
	v_mov_b32_e32 v98, v2
	v_mov_b32_e32 v99, v2
	v_mov_b32_e32 v100, v2
	v_mov_b32_e32 v101, v2
	v_mov_b32_e32 v102, v2
	v_mov_b32_e32 v103, v2
	v_mov_b32_e32 v104, v2
	v_mov_b32_e32 v105, v2
	v_mov_b32_e32 v106, v2
	v_mov_b32_e32 v107, v2
	v_mov_b32_e32 v108, v2
	v_mov_b32_e32 v109, v2
	v_mov_b32_e32 v110, v2
	v_mov_b32_e32 v111, v2
	v_mov_b32_e32 v112, v2
	v_mov_b32_e32 v113, v2
	v_mov_b32_e32 v114, v2
	v_mov_b32_e32 v115, v2
	v_mov_b32_e32 v116, v2
	v_mov_b32_e32 v117, v2
	v_mov_b32_e32 v118, v2
	v_mov_b32_e32 v119, v2
	v_mov_b32_e32 v120, v2
	v_mov_b32_e32 v121, v2
	v_mov_b32_e32 v122, v2
	v_mov_b32_e32 v123, v2
	v_mov_b32_e32 v124, v2
	v_mov_b32_e32 v125, v2
	v_mov_b32_e32 v126, v2
	v_mov_b32_e32 v127, v2
	v_mov_b32_e32 v128, v2
	v_mov_b32_e32 v129, v2
	.p2alignl 6, 3212836864
	v_add_u32_e32 v251, 0x80, v140

.LBB0_1478:
	s_ashr_i32 s31, s30, 31
	s_lshl_b64 s[12:13], s[30:31], 19
	s_add_u32 s36, s3, s12
	s_addc_u32 s37, s19, s13
	s_and_b64 s[12:13], s[4:5], exec
	s_cselect_b32 s31, s37, s1
	s_cselect_b32 s43, s36, s0
	s_ashr_i32 s29, s28, 31
	s_lshl_b64 s[12:13], s[28:29], 19
	s_add_u32 s38, s33, s12
	s_addc_u32 s39, s48, s13
	s_and_b64 s[12:13], s[4:5], exec
	s_cselect_b32 s29, s39, s45
	s_cselect_b32 s67, s38, s44
	s_add_u32 s0, s0, 0x40080
	s_addc_u32 s1, s1, 0
	s_add_u32 s68, s44, 0x100
	v_mov_b32_e32 v2, 0
	s_addc_u32 s69, s45, 0
	s_mov_b32 s12, -2
	v_mov_b32_e32 v3, v2
	v_mov_b32_e32 v4, v2
	v_mov_b32_e32 v5, v2
	v_mov_b32_e32 v6, v2
	v_mov_b32_e32 v7, v2
	v_mov_b32_e32 v8, v2
	v_mov_b32_e32 v9, v2
	v_mov_b32_e32 v18, v2
	v_mov_b32_e32 v19, v2
	v_mov_b32_e32 v20, v2
	v_mov_b32_e32 v21, v2
	v_mov_b32_e32 v22, v2
	v_mov_b32_e32 v23, v2
	v_mov_b32_e32 v24, v2
	v_mov_b32_e32 v25, v2
	v_mov_b32_e32 v34, v2
	v_mov_b32_e32 v35, v2
	v_mov_b32_e32 v36, v2
	v_mov_b32_e32 v37, v2
	v_mov_b32_e32 v38, v2
	v_mov_b32_e32 v39, v2
	v_mov_b32_e32 v40, v2
	v_mov_b32_e32 v41, v2
	v_mov_b32_e32 v50, v2
	v_mov_b32_e32 v51, v2
	v_mov_b32_e32 v52, v2
	v_mov_b32_e32 v53, v2
	v_mov_b32_e32 v54, v2
	v_mov_b32_e32 v55, v2
	v_mov_b32_e32 v56, v2
	v_mov_b32_e32 v57, v2
	v_mov_b32_e32 v10, v2
	v_mov_b32_e32 v11, v2
	v_mov_b32_e32 v12, v2
	v_mov_b32_e32 v13, v2
	v_mov_b32_e32 v14, v2
	v_mov_b32_e32 v15, v2
	v_mov_b32_e32 v16, v2
	v_mov_b32_e32 v17, v2
	v_mov_b32_e32 v26, v2
	v_mov_b32_e32 v27, v2
	v_mov_b32_e32 v28, v2
	v_mov_b32_e32 v29, v2
	v_mov_b32_e32 v30, v2
	v_mov_b32_e32 v31, v2
	v_mov_b32_e32 v32, v2
	v_mov_b32_e32 v33, v2
	v_mov_b32_e32 v42, v2
	v_mov_b32_e32 v43, v2
	v_mov_b32_e32 v44, v2
	v_mov_b32_e32 v45, v2
	v_mov_b32_e32 v46, v2
	v_mov_b32_e32 v47, v2
	v_mov_b32_e32 v48, v2
	v_mov_b32_e32 v49, v2
	v_mov_b32_e32 v58, v2
	v_mov_b32_e32 v59, v2
	v_mov_b32_e32 v60, v2
	v_mov_b32_e32 v61, v2
	v_mov_b32_e32 v62, v2
	v_mov_b32_e32 v63, v2
	v_mov_b32_e32 v64, v2
	v_mov_b32_e32 v65, v2
	v_mov_b32_e32 v66, v2
	v_mov_b32_e32 v67, v2
	v_mov_b32_e32 v68, v2
	v_mov_b32_e32 v69, v2
	v_mov_b32_e32 v70, v2
	v_mov_b32_e32 v71, v2
	v_mov_b32_e32 v72, v2
	v_mov_b32_e32 v73, v2
	v_mov_b32_e32 v82, v2
	v_mov_b32_e32 v83, v2
	v_mov_b32_e32 v84, v2
	v_mov_b32_e32 v85, v2
	v_mov_b32_e32 v86, v2
	v_mov_b32_e32 v87, v2
	v_mov_b32_e32 v88, v2
	v_mov_b32_e32 v89, v2
	v_mov_b32_e32 v114, v2
	v_mov_b32_e32 v115, v2
	v_mov_b32_e32 v116, v2
	v_mov_b32_e32 v117, v2
	v_mov_b32_e32 v118, v2
	v_mov_b32_e32 v119, v2
	v_mov_b32_e32 v120, v2
	v_mov_b32_e32 v121, v2
	v_mov_b32_e32 v130, v2
	v_mov_b32_e32 v131, v2
	v_mov_b32_e32 v132, v2
	v_mov_b32_e32 v133, v2
	v_mov_b32_e32 v134, v2
	v_mov_b32_e32 v135, v2
	v_mov_b32_e32 v136, v2
	v_mov_b32_e32 v137, v2
	v_mov_b32_e32 v74, v2
	v_mov_b32_e32 v75, v2
	v_mov_b32_e32 v76, v2
	v_mov_b32_e32 v77, v2
	v_mov_b32_e32 v78, v2
	v_mov_b32_e32 v79, v2
	v_mov_b32_e32 v80, v2
	v_mov_b32_e32 v81, v2
	v_mov_b32_e32 v90, v2
	v_mov_b32_e32 v91, v2
	v_mov_b32_e32 v92, v2
	v_mov_b32_e32 v93, v2
	v_mov_b32_e32 v94, v2
	v_mov_b32_e32 v95, v2
	v_mov_b32_e32 v96, v2
	v_mov_b32_e32 v97, v2
	v_mov_b32_e32 v122, v2
	v_mov_b32_e32 v123, v2
	v_mov_b32_e32 v124, v2
	v_mov_b32_e32 v125, v2
	v_mov_b32_e32 v126, v2
	v_mov_b32_e32 v127, v2
	v_mov_b32_e32 v128, v2
	v_mov_b32_e32 v129, v2
	v_mov_b32_e32 v138, v2
	v_mov_b32_e32 v139, v2
	v_mov_b32_e32 v140, v2
	v_mov_b32_e32 v141, v2
	v_mov_b32_e32 v142, v2
	v_mov_b32_e32 v143, v2
	v_mov_b32_e32 v144, v2
	v_mov_b32_e32 v145, v2
	.p2alignl 6, 3212836864
	v_add_u32_e32 v251, 0x80, v152

.LBB0_1560:
	s_add_u32 s27, s30, 0x100
	v_mov_b32_e32 v2, 0
	s_addc_u32 s67, s31, 0
	s_mov_b32 s12, -2
	s_waitcnt lgkmcnt(0)
	v_mov_b32_e32 v3, v2
	v_mov_b32_e32 v4, v2
	v_mov_b32_e32 v5, v2
	v_mov_b32_e32 v6, v2
	v_mov_b32_e32 v7, v2
	v_mov_b32_e32 v8, v2
	v_mov_b32_e32 v9, v2
	v_mov_b32_e32 v10, v2
	v_mov_b32_e32 v11, v2
	v_mov_b32_e32 v12, v2
	v_mov_b32_e32 v13, v2
	v_mov_b32_e32 v14, v2
	v_mov_b32_e32 v15, v2
	v_mov_b32_e32 v16, v2
	v_mov_b32_e32 v17, v2
	v_mov_b32_e32 v18, v2
	v_mov_b32_e32 v19, v2
	v_mov_b32_e32 v20, v2
	v_mov_b32_e32 v21, v2
	v_mov_b32_e32 v22, v2
	v_mov_b32_e32 v23, v2
	v_mov_b32_e32 v24, v2
	v_mov_b32_e32 v25, v2
	v_mov_b32_e32 v26, v2
	v_mov_b32_e32 v27, v2
	v_mov_b32_e32 v28, v2
	v_mov_b32_e32 v29, v2
	v_mov_b32_e32 v30, v2
	v_mov_b32_e32 v31, v2
	v_mov_b32_e32 v32, v2
	v_mov_b32_e32 v33, v2
	v_mov_b32_e32 v66, v2
	v_mov_b32_e32 v67, v2
	v_mov_b32_e32 v68, v2
	v_mov_b32_e32 v69, v2
	v_mov_b32_e32 v70, v2
	v_mov_b32_e32 v71, v2
	v_mov_b32_e32 v72, v2
	v_mov_b32_e32 v73, v2
	v_mov_b32_e32 v74, v2
	v_mov_b32_e32 v75, v2
	v_mov_b32_e32 v76, v2
	v_mov_b32_e32 v77, v2
	v_mov_b32_e32 v78, v2
	v_mov_b32_e32 v79, v2
	v_mov_b32_e32 v80, v2
	v_mov_b32_e32 v81, v2
	v_mov_b32_e32 v82, v2
	v_mov_b32_e32 v83, v2
	v_mov_b32_e32 v84, v2
	v_mov_b32_e32 v85, v2
	v_mov_b32_e32 v86, v2
	v_mov_b32_e32 v87, v2
	v_mov_b32_e32 v88, v2
	v_mov_b32_e32 v89, v2
	v_mov_b32_e32 v90, v2
	v_mov_b32_e32 v91, v2
	v_mov_b32_e32 v92, v2
	v_mov_b32_e32 v93, v2
	v_mov_b32_e32 v94, v2
	v_mov_b32_e32 v95, v2
	v_mov_b32_e32 v96, v2
	v_mov_b32_e32 v97, v2
	v_mov_b32_e32 v34, v2
	v_mov_b32_e32 v35, v2
	v_mov_b32_e32 v36, v2
	v_mov_b32_e32 v37, v2
	v_mov_b32_e32 v38, v2
	v_mov_b32_e32 v39, v2
	v_mov_b32_e32 v40, v2
	v_mov_b32_e32 v41, v2
	v_mov_b32_e32 v42, v2
	v_mov_b32_e32 v43, v2
	v_mov_b32_e32 v44, v2
	v_mov_b32_e32 v45, v2
	v_mov_b32_e32 v46, v2
	v_mov_b32_e32 v47, v2
	v_mov_b32_e32 v48, v2
	v_mov_b32_e32 v49, v2
	v_mov_b32_e32 v50, v2
	v_mov_b32_e32 v51, v2
	v_mov_b32_e32 v52, v2
	v_mov_b32_e32 v53, v2
	v_mov_b32_e32 v54, v2
	v_mov_b32_e32 v55, v2
	v_mov_b32_e32 v56, v2
	v_mov_b32_e32 v57, v2
	v_mov_b32_e32 v58, v2
	v_mov_b32_e32 v59, v2
	v_mov_b32_e32 v60, v2
	v_mov_b32_e32 v61, v2
	v_mov_b32_e32 v62, v2
	v_mov_b32_e32 v63, v2
	v_mov_b32_e32 v64, v2
	v_mov_b32_e32 v65, v2
	v_mov_b32_e32 v98, v2
	v_mov_b32_e32 v99, v2
	v_mov_b32_e32 v100, v2
	v_mov_b32_e32 v101, v2
	v_mov_b32_e32 v102, v2
	v_mov_b32_e32 v103, v2
	v_mov_b32_e32 v104, v2
	v_mov_b32_e32 v105, v2
	v_mov_b32_e32 v106, v2
	v_mov_b32_e32 v107, v2
	v_mov_b32_e32 v108, v2
	v_mov_b32_e32 v109, v2
	v_mov_b32_e32 v110, v2
	v_mov_b32_e32 v111, v2
	v_mov_b32_e32 v112, v2
	v_mov_b32_e32 v113, v2
	v_mov_b32_e32 v114, v2
	v_mov_b32_e32 v115, v2
	v_mov_b32_e32 v116, v2
	v_mov_b32_e32 v117, v2
	v_mov_b32_e32 v118, v2
	v_mov_b32_e32 v119, v2
	v_mov_b32_e32 v120, v2
	v_mov_b32_e32 v121, v2
	v_mov_b32_e32 v122, v2
	v_mov_b32_e32 v123, v2
	v_mov_b32_e32 v124, v2
	v_mov_b32_e32 v125, v2
	v_mov_b32_e32 v126, v2
	v_mov_b32_e32 v127, v2
	v_mov_b32_e32 v128, v2
	v_mov_b32_e32 v129, v2
	.p2alignl 6, 3212836864
	v_add_u32_e32 v251, 0x80, v140
	v_add_u32_e32 v252, 0x80, v144
	v_add_u32_e32 v253, 0x80, v138
	v_add_u32_e32 v254, 0x80, v142

.LBB0_1605:
	s_add_u32 s9, s48, 0x100
	v_mov_b32_e32 v42, 0
	s_addc_u32 s77, s49, 0
	s_mov_b32 s12, -2
	v_mov_b32_e32 v43, v42
	v_mov_b32_e32 v44, v42
	v_mov_b32_e32 v45, v42
	v_mov_b32_e32 v46, v42
	v_mov_b32_e32 v47, v42
	v_mov_b32_e32 v48, v42
	v_mov_b32_e32 v49, v42
	v_mov_b32_e32 v2, v42
	v_mov_b32_e32 v3, v42
	v_mov_b32_e32 v4, v42
	v_mov_b32_e32 v5, v42
	v_mov_b32_e32 v6, v42
	v_mov_b32_e32 v7, v42
	v_mov_b32_e32 v8, v42
	v_mov_b32_e32 v9, v42
	v_mov_b32_e32 v66, v42
	v_mov_b32_e32 v67, v42
	v_mov_b32_e32 v68, v42
	v_mov_b32_e32 v69, v42
	v_mov_b32_e32 v78, v42
	v_mov_b32_e32 v79, v42
	v_mov_b32_e32 v80, v42
	v_mov_b32_e32 v81, v42
	v_mov_b32_e32 v18, v42
	v_mov_b32_e32 v19, v42
	v_mov_b32_e32 v20, v42
	v_mov_b32_e32 v21, v42
	v_mov_b32_e32 v22, v42
	v_mov_b32_e32 v23, v42
	v_mov_b32_e32 v24, v42
	v_mov_b32_e32 v25, v42
	v_mov_b32_e32 v98, v42
	v_mov_b32_e32 v99, v42
	v_mov_b32_e32 v100, v42
	v_mov_b32_e32 v101, v42
	v_mov_b32_e32 v102, v42
	v_mov_b32_e32 v103, v42
	v_mov_b32_e32 v104, v42
	v_mov_b32_e32 v105, v42
	v_mov_b32_e32 v10, v42
	v_mov_b32_e32 v11, v42
	v_mov_b32_e32 v12, v42
	v_mov_b32_e32 v13, v42
	v_mov_b32_e32 v14, v42
	v_mov_b32_e32 v15, v42
	v_mov_b32_e32 v16, v42
	v_mov_b32_e32 v17, v42
	v_mov_b32_e32 v114, v42
	v_mov_b32_e32 v115, v42
	v_mov_b32_e32 v116, v42
	v_mov_b32_e32 v117, v42
	v_mov_b32_e32 v118, v42
	v_mov_b32_e32 v119, v42
	v_mov_b32_e32 v120, v42
	v_mov_b32_e32 v121, v42
	v_mov_b32_e32 v26, v42
	v_mov_b32_e32 v27, v42
	v_mov_b32_e32 v28, v42
	v_mov_b32_e32 v29, v42
	v_mov_b32_e32 v30, v42
	v_mov_b32_e32 v31, v42
	v_mov_b32_e32 v32, v42
	v_mov_b32_e32 v33, v42
	v_mov_b32_e32 v82, v42
	v_mov_b32_e32 v83, v42
	v_mov_b32_e32 v84, v42
	v_mov_b32_e32 v85, v42
	v_mov_b32_e32 v86, v42
	v_mov_b32_e32 v87, v42
	v_mov_b32_e32 v88, v42
	v_mov_b32_e32 v89, v42
	v_mov_b32_e32 v34, v42
	v_mov_b32_e32 v35, v42
	v_mov_b32_e32 v36, v42
	v_mov_b32_e32 v37, v42
	v_mov_b32_e32 v38, v42
	v_mov_b32_e32 v39, v42
	v_mov_b32_e32 v40, v42
	v_mov_b32_e32 v41, v42
	v_mov_b32_e32 v90, v42
	v_mov_b32_e32 v91, v42
	v_mov_b32_e32 v92, v42
	v_mov_b32_e32 v93, v42
	v_mov_b32_e32 v94, v42
	v_mov_b32_e32 v95, v42
	v_mov_b32_e32 v96, v42
	v_mov_b32_e32 v97, v42
	v_mov_b32_e32 v58, v42
	v_mov_b32_e32 v59, v42
	v_mov_b32_e32 v60, v42
	v_mov_b32_e32 v61, v42
	v_mov_b32_e32 v62, v42
	v_mov_b32_e32 v63, v42
	v_mov_b32_e32 v64, v42
	v_mov_b32_e32 v65, v42
	v_mov_b32_e32 v122, v42
	v_mov_b32_e32 v123, v42
	v_mov_b32_e32 v124, v42
	v_mov_b32_e32 v125, v42
	v_mov_b32_e32 v126, v42
	v_mov_b32_e32 v127, v42
	v_mov_b32_e32 v128, v42
	v_mov_b32_e32 v129, v42
	v_mov_b32_e32 v50, v42
	v_mov_b32_e32 v51, v42
	v_mov_b32_e32 v52, v42
	v_mov_b32_e32 v53, v42
	v_mov_b32_e32 v54, v42
	v_mov_b32_e32 v55, v42
	v_mov_b32_e32 v56, v42
	v_mov_b32_e32 v57, v42
	v_mov_b32_e32 v130, v42
	v_mov_b32_e32 v131, v42
	v_mov_b32_e32 v132, v42
	v_mov_b32_e32 v133, v42
	v_mov_b32_e32 v134, v42
	v_mov_b32_e32 v135, v42
	v_mov_b32_e32 v136, v42
	v_mov_b32_e32 v137, v42
	v_mov_b32_e32 v70, v42
	v_mov_b32_e32 v71, v42
	v_mov_b32_e32 v72, v42
	v_mov_b32_e32 v73, v42
	v_mov_b32_e32 v74, v42
	v_mov_b32_e32 v75, v42
	v_mov_b32_e32 v76, v42
	v_mov_b32_e32 v77, v42
	.p2alignl 6, 3212836864
	v_add_u32_e32 v251, 0x80, v144
	v_add_u32_e32 v252, 0x80, v148
	v_add_u32_e32 v253, 0x80, v142
	v_add_u32_e32 v254, 0x80, v146
